# final RMSNorm phase: row loop software-pipelined (next row loads issued before current stores, counted wait)
# baseline (speedup 1.0000x reference)
; __device__ __forceinline__ float rstd_of(const float* rss, int row) { return __builtin_amdgcn_rsqf((float)((const unsigned*)rss)[row] * (1.0f / (256.0f * 1024.0f)) + RMS_EPS); }
; DI void final_phase(const Args& a, int gw, int NGW, int lane) {
;     const float* rss = (const float*)(a.ws + WS_CTL) + CW_RSS + 4 * (size_t)M; const f32x4* gf = (const f32x4*)a.in[15] + lane; const bf16_t* XB = (const bf16_t*)(a.ws + WS_XB);
;     f32x4 gv[4];
; #pragma unroll
;     for (int j = 0; j < 4; ++j) gv[j] = gf[64 * j];
;     for (int mrow = gw; mrow < M; mrow += NGW) {
;         const float rs = pg8::rstd_of(rss, mrow);
;         f32x4* xr = (f32x4*)(a.out + (size_t)mrow * D) + lane; const u32x2* xb = (const u32x2*)(XB + (size_t)mrow * D) + lane;
;         u32x2 wv[4];
; #pragma unroll
;         for (int j = 0; j < 4; ++j) wv[j] = xb[64 * j];
; #pragma unroll
;         for (int j = 0; j < 4; ++j) { const u32x2 w = wv[j]; f32x4 v = (f32x4){__uint_as_float(w.x << 16), __uint_as_float(w.x & 0xffff0000u), __uint_as_float(w.y << 16), __uint_as_float(w.y & 0xffff0000u)}; v = v * rs * gv[j]; xr[64 * j] = v; }
;     }
.LBB0_688:
	s_and_b64 vcc, exec, s[0:1]
	s_cbranch_vccz .LBB0_692
	s_cmpk_gt_i32 s52, 0x7fff
	s_cbranch_scc1 .LBB0_692
	v_readlane_b32 s0, v254, 18
	v_lshlrev_b32_e32 v20, 4, v249
	v_readlane_b32 s1, v254, 19
	s_waitcnt lgkmcnt(0)
	s_nop 3
	global_load_dwordx4 v[4:7], v20, s[0:1]
	global_load_dwordx4 v[8:11], v20, s[0:1] offset:1024
	global_load_dwordx4 v[12:15], v20, s[0:1] offset:2048
	global_load_dwordx4 v[16:19], v20, s[0:1] offset:3072
	s_ashr_i32 s53, s52, 31
	s_lshl_b64 s[0:1], s[52:53], 2
	v_readlane_b32 s2, v254, 20
	v_readlane_b32 s3, v254, 21
	s_add_u32 s6, s0, 0xc0000
	s_addc_u32 s7, s1, 0
	s_ashr_i32 s59, s58, 31
	s_lshl_b64 s[2:3], s[52:53], 11
	s_lshl_b64 s[0:1], s[58:59], 2
	v_lshl_or_b32 v0, v249, 3, s2
	v_mov_b32_e32 v1, s3
	s_lshl_b64 s[2:3], s[58:59], 11
	s_lshl_b64 s[4:5], s[52:53], 12
	v_readlane_b32 s8, v254, 17
	s_add_u32 s4, s8, s4
	v_readlane_b32 s8, v254, 22
	v_mov_b32_e32 v21, v2
	s_addc_u32 s5, s8, s5
	v_lshl_add_u64 v[20:21], s[4:5], 0, v[20:21]
	s_lshl_b64 s[4:5], s[58:59], 12
	s_mov_b32 s8, s52
	s_add_u32 s10, s66, s6
	s_addc_u32 s11, s67, s7
	global_load_dword v44, v2, s[10:11]
	v_lshl_add_u64 v[54:55], s[66:67], 0, v[0:1]
	v_add_co_u32_e32 v54, vcc, 0x5400000, v54
	s_nop 1
	v_addc_co_u32_e32 v55, vcc, 0, v55, vcc
	global_load_dwordx2 v[46:47], v[54:55], off
	global_load_dwordx2 v[48:49], v[54:55], off offset:512
	global_load_dwordx2 v[50:51], v[54:55], off offset:1024
	global_load_dwordx2 v[52:53], v[54:55], off offset:1536
	s_waitcnt vmcnt(0)
.Lfin_top:
	v_mov_b32_e32 v3, v44
	v_mov_b32_e32 v24, v46
	v_mov_b32_e32 v25, v47
	v_mov_b32_e32 v26, v48
	v_mov_b32_e32 v27, v49
	v_mov_b32_e32 v28, v50
	v_mov_b32_e32 v29, v51
	v_mov_b32_e32 v22, v52
	v_mov_b32_e32 v23, v53
	s_add_u32 s6, s6, s0
	s_addc_u32 s7, s7, s1
	v_lshl_add_u64 v[0:1], v[0:1], 0, s[2:3]
	s_add_i32 s8, s8, s58
	s_cmpk_gt_i32 s8, 0x7fff
	s_cbranch_scc1 .Lfin_nopf
	s_add_u32 s10, s66, s6
	s_addc_u32 s11, s67, s7
	global_load_dword v44, v2, s[10:11]
	v_lshl_add_u64 v[54:55], s[66:67], 0, v[0:1]
	v_add_co_u32_e32 v54, vcc, 0x5400000, v54
	s_nop 1
	v_addc_co_u32_e32 v55, vcc, 0, v55, vcc
	global_load_dwordx2 v[46:47], v[54:55], off
	global_load_dwordx2 v[48:49], v[54:55], off offset:512
	global_load_dwordx2 v[50:51], v[54:55], off offset:1024
	global_load_dwordx2 v[52:53], v[54:55], off offset:1536
.Lfin_nopf:
	v_cvt_f32_u32_e32 v3, v3
	v_lshlrev_b32_e32 v30, 16, v24
	v_fmamk_f32 v3, v3, 0x36800000, v237
	v_rsq_f32_e32 v38, v3
	v_and_b32_e32 v31, 0xffff0000, v24
	v_lshlrev_b32_e32 v24, 16, v25
	v_and_b32_e32 v25, 0xffff0000, v25
	v_lshlrev_b32_e32 v32, 16, v26
	v_and_b32_e32 v33, 0xffff0000, v26
	v_lshlrev_b32_e32 v26, 16, v27
	v_and_b32_e32 v27, 0xffff0000, v27
	v_lshlrev_b32_e32 v34, 16, v28
	v_and_b32_e32 v35, 0xffff0000, v28
	v_lshlrev_b32_e32 v28, 16, v29
	v_and_b32_e32 v29, 0xffff0000, v29
	v_lshlrev_b32_e32 v36, 16, v22
	v_and_b32_e32 v37, 0xffff0000, v22
	v_lshlrev_b32_e32 v22, 16, v23
	v_and_b32_e32 v23, 0xffff0000, v23
	v_pk_mul_f32 v[30:31], v[38:39], v[30:31] op_sel_hi:[0,1]
	v_pk_mul_f32 v[24:25], v[38:39], v[24:25] op_sel_hi:[0,1]
	v_pk_mul_f32 v[32:33], v[38:39], v[32:33] op_sel_hi:[0,1]
	v_pk_mul_f32 v[26:27], v[38:39], v[26:27] op_sel_hi:[0,1]
	v_pk_mul_f32 v[34:35], v[38:39], v[34:35] op_sel_hi:[0,1]
	v_pk_mul_f32 v[40:41], v[38:39], v[28:29] op_sel_hi:[0,1]
	v_pk_mul_f32 v[42:43], v[38:39], v[36:37] op_sel_hi:[0,1]
	v_pk_mul_f32 v[36:37], v[38:39], v[22:23] op_sel_hi:[0,1]
	v_pk_mul_f32 v[24:25], v[6:7], v[24:25]
	v_pk_mul_f32 v[22:23], v[4:5], v[30:31]
	v_pk_mul_f32 v[28:29], v[10:11], v[26:27]
	v_pk_mul_f32 v[26:27], v[8:9], v[32:33]
	v_pk_mul_f32 v[32:33], v[14:15], v[40:41]
	v_pk_mul_f32 v[30:31], v[12:13], v[34:35]
	v_pk_mul_f32 v[36:37], v[18:19], v[36:37]
	v_pk_mul_f32 v[34:35], v[16:17], v[42:43]
	global_store_dwordx4 v[20:21], v[22:25], off offset:-3072
	global_store_dwordx4 v[20:21], v[26:29], off offset:-2048
	global_store_dwordx4 v[20:21], v[30:33], off offset:-1024
	global_store_dwordx4 v[20:21], v[34:37], off
	v_lshl_add_u64 v[20:21], v[20:21], 0, s[4:5]
	s_cmpk_gt_i32 s8, 0x7fff
	s_cbranch_scc1 .LBB0_692
	s_waitcnt vmcnt(4)
	s_branch .Lfin_top
